# gated GEMM A epilogue: the 16 gate loads issued together with counted vmcnt (was load + vmcnt(0) per 16-row block)
# speedup vs baseline: 1.0137x; 1.0137x over previous
; #define PG8_STAGE(bufoff, gbase, voff) do { _Pragma("unroll") for (int _i = 0; _i < 2; ++_i) \
;         __builtin_amdgcn_global_load_lds((const unsigned*)((const char*)(gbase) + (voff)[_i]), (PG8_LAS unsigned*)(lds + (bufoff) + ldsw + _i * 8192), 16, 0, 0); } while (0)
; #define PG8_LDA(dst, b, h) do { _Pragma("unroll") for (int m = 0; m < 4; ++m) _Pragma("unroll") for (int k = 0; k < 2; ++k) dst[m][k] = *(const PG8_LAS bf16x8*)(lds + PG8_SA(b, h) + aoff + m * 2048 + k * 1024); } while (0)
; #define PG8_LDB(dst, b, h) do { _Pragma("unroll") for (int n = 0; n < 2; ++n) _Pragma("unroll") for (int k = 0; k < 2; ++k) dst[n][k] = *(const PG8_LAS bf16x8*)(lds + PG8_SB(b, h) + boff + n * 2048 + k * 1024); } while (0)
; #define PG8_MMA(ai, bj, At, Bt) do { __builtin_amdgcn_s_setprio(1); _Pragma("unroll") for (int m = 0; m < 4; ++m) _Pragma("unroll") for (int n = 0; n < 2; ++n) _Pragma("unroll") for (int k = 0; k < 2; ++k) \
;         acc[ai][bj][m][n] = __builtin_amdgcn_mfma_f32_16x16x32_bf16(Bt[n][k], At[m][k], acc[ai][bj][m][n], 0, 0, 0); __builtin_amdgcn_s_setprio(0); } while (0)
; #define PG8_WAIT_V(n) asm volatile("s_waitcnt vmcnt(" #n ")" ::: "memory")
; #define PG8_WAIT_L(n) asm volatile("s_waitcnt lgkmcnt(" #n ")" ::: "memory")
; #define PG8_BAR __builtin_amdgcn_s_barrier()
; #define PG8_SCHED __builtin_amdgcn_sched_barrier(0)
; template <class Epi, class Sched>
; __device__ __forceinline__ void gemm_phase(PG8_LAS unsigned char* lds, const Gemm g, const Sched& S, const Epi& E) {
;     ...
;             PG8_LDB(B0, 0, 0); PG8_SCHED; PG8_LDA(At, 0, 0); PG8_STAGE(PG8_SA(1, 1), a1 + hstep, voffA);
;             PG8_WAIT_L(8); PG8_BAR; PG8_WAIT_L(0); PG8_MMA(0, 0, At, B0); PG8_BAR; PG8_SCHED;
;             PG8_LDB(B1, 0, 1); PG8_STAGE(PG8_SB(0, 0), b2, voffB);
;             PG8_BAR; PG8_WAIT_L(0); PG8_MMA(0, 1, At, B1); PG8_BAR;
;             PG8_LDA(At, 0, 1); PG8_STAGE(PG8_SA(0, 0), a2, voffA);
;             PG8_BAR; PG8_WAIT_L(0); PG8_MMA(1, 0, At, B0); PG8_BAR; PG8_SCHED;
;             PG8_STAGE(PG8_SB(0, 1), b2 + hstep, voffB);
;             PG8_WAIT_V(6); PG8_BAR; PG8_MMA(1, 1, At, B1); PG8_BAR;
.LBB0_991:
	ds_read_b128 v[144:147], v153
	ds_read_b128 v[156:159], v153 offset:1024
	ds_read_b128 v[160:163], v153 offset:2048
	ds_read_b128 v[164:167], v153 offset:3072
	s_add_u32 s20, s18, 0xfffc0080
	s_addc_u32 s21, s19, -1
	s_cmp_eq_u32 s47, 12
	s_cselect_b32 s23, s11, s21
	s_cselect_b32 s22, s43, s20
	s_cselect_b32 s21, s9, s46
	s_cselect_b32 s20, s44, s45
	s_add_i32 m0, s17, 0xc000
	ds_read_b128 v[168:171], v154
	ds_read_b128 v[172:175], v154 offset:1024
	ds_read_b128 v[182:185], v154 offset:2048
	ds_read_b128 v[190:193], v154 offset:3072
	ds_read_b128 v[194:197], v154 offset:4096
	ds_read_b128 v[198:201], v154 offset:5120
	ds_read_b128 v[202:205], v154 offset:6144
	ds_read_b128 v[206:209], v154 offset:7168
	global_load_lds_dwordx4 v136, s[18:19]
	s_nop 1
	s_add_i32 m0, s17, 0xe000
	s_nop 0
	global_load_lds_dwordx4 v138, s[18:19]
	s_waitcnt lgkmcnt(8)
	ds_read_b128 v[210:213], v155
	ds_read_b128 v[214:217], v155 offset:1024
	ds_read_b128 v[218:221], v155 offset:2048
	ds_read_b128 v[222:225], v155 offset:3072
	s_waitcnt vmcnt(8) lgkmcnt(0)
	s_barrier
	v_mfma_f32_16x16x32_bf16 v[124:127], v[144:147], v[168:171], v[124:127]
	v_mfma_f32_16x16x32_bf16 v[120:123], v[160:163], v[168:171], v[120:123]
	v_mfma_f32_16x16x32_bf16 v[112:115], v[144:147], v[182:185], v[112:115]
	v_mfma_f32_16x16x32_bf16 v[104:107], v[160:163], v[182:185], v[104:107]
	v_mfma_f32_16x16x32_bf16 v[96:99], v[144:147], v[194:197], v[96:99]
	v_mfma_f32_16x16x32_bf16 v[88:91], v[160:163], v[194:197], v[88:91]
	v_mfma_f32_16x16x32_bf16 v[80:83], v[144:147], v[202:205], v[80:83]
	v_mfma_f32_16x16x32_bf16 v[72:75], v[160:163], v[202:205], v[72:75]
	v_mfma_f32_16x16x32_bf16 v[124:127], v[156:159], v[172:175], v[124:127]
	v_mfma_f32_16x16x32_bf16 v[120:123], v[164:167], v[172:175], v[120:123]
	v_mfma_f32_16x16x32_bf16 v[112:115], v[156:159], v[190:193], v[112:115]
	v_mfma_f32_16x16x32_bf16 v[104:107], v[164:167], v[190:193], v[104:107]
	v_mfma_f32_16x16x32_bf16 v[96:99], v[156:159], v[198:201], v[96:99]
	v_mfma_f32_16x16x32_bf16 v[88:91], v[164:167], v[198:201], v[88:91]
	v_mfma_f32_16x16x32_bf16 v[80:83], v[156:159], v[206:209], v[80:83]
	v_mfma_f32_16x16x32_bf16 v[72:75], v[164:167], v[206:209], v[72:75]
	v_mfma_f32_16x16x32_bf16 v[116:119], v[210:213], v[168:171], v[116:119]
	v_mfma_f32_16x16x32_bf16 v[108:111], v[218:221], v[168:171], v[108:111]
	v_mfma_f32_16x16x32_bf16 v[100:103], v[210:213], v[182:185], v[100:103]
	v_mfma_f32_16x16x32_bf16 v[92:95], v[218:221], v[182:185], v[92:95]
	v_mfma_f32_16x16x32_bf16 v[84:87], v[210:213], v[194:197], v[84:87]
	v_mfma_f32_16x16x32_bf16 v[76:79], v[218:221], v[194:197], v[76:79]
	v_mfma_f32_16x16x32_bf16 v[68:71], v[210:213], v[202:205], v[68:71]
	v_mfma_f32_16x16x32_bf16 v[64:67], v[218:221], v[202:205], v[64:67]
	v_mfma_f32_16x16x32_bf16 v[116:119], v[214:217], v[172:175], v[116:119]
	v_mfma_f32_16x16x32_bf16 v[108:111], v[222:225], v[172:175], v[108:111]
	v_mfma_f32_16x16x32_bf16 v[100:103], v[214:217], v[190:193], v[100:103]
	v_mfma_f32_16x16x32_bf16 v[92:95], v[222:225], v[190:193], v[92:95]
	v_mfma_f32_16x16x32_bf16 v[84:87], v[214:217], v[198:201], v[84:87]
	v_mfma_f32_16x16x32_bf16 v[76:79], v[222:225], v[198:201], v[76:79]
	v_mfma_f32_16x16x32_bf16 v[68:71], v[214:217], v[206:209], v[68:71]
	v_mfma_f32_16x16x32_bf16 v[64:67], v[222:225], v[206:209], v[64:67]
	s_barrier
	ds_read_b128 v[168:171], v154 offset:16384
	ds_read_b128 v[172:175], v154 offset:17408
	ds_read_b128 v[182:185], v154 offset:18432
	ds_read_b128 v[190:193], v154 offset:19456
	ds_read_b128 v[194:197], v154 offset:20480
	ds_read_b128 v[198:201], v154 offset:21504
	ds_read_b128 v[202:205], v154 offset:22528
	ds_read_b128 v[206:209], v154 offset:23552
	s_add_i32 s48, s39, s29
	s_add_u32 s98, s20, s6
	s_addc_u32 s99, s21, s7
	s_mov_b32 m0, s48
	s_nop 0
	global_load_lds_dwordx4 v130, s[20:21]
	s_nop 1
	s_add_i32 m0, s48, 0x2000
	s_nop 0
	global_load_lds_dwordx4 v134, s[20:21]
	s_nop 1
	s_mov_b32 m0, s17
	s_add_u32 s100, s22, s6
	s_addc_u32 s101, s23, s7
	global_load_lds_dwordx4 v128, s[22:23]
	s_nop 1
	s_mov_b32 m0, s30
	s_nop 0
	global_load_lds_dwordx4 v132, s[22:23]
	s_add_u32 s48, s20, 0x40000
	s_addc_u32 s49, s21, 0
	s_add_i32 s50, s40, s29
	s_mov_b32 m0, s50
	s_nop 0
	global_load_lds_dwordx4 v130, s[48:49]
	s_nop 1
	s_add_i32 m0, s50, 0x2000
	s_nop 0
	global_load_lds_dwordx4 v134, s[48:49]
	s_waitcnt vmcnt(8) lgkmcnt(0)
	s_barrier
	v_mfma_f32_16x16x32_bf16 v[60:63], v[144:147], v[168:171], v[60:63]
	v_mfma_f32_16x16x32_bf16 v[56:59], v[160:163], v[168:171], v[56:59]
	v_mfma_f32_16x16x32_bf16 v[48:51], v[144:147], v[182:185], v[48:51]
	v_mfma_f32_16x16x32_bf16 v[40:43], v[160:163], v[182:185], v[40:43]
	v_mfma_f32_16x16x32_bf16 v[32:35], v[144:147], v[194:197], v[32:35]
	v_mfma_f32_16x16x32_bf16 v[24:27], v[160:163], v[194:197], v[24:27]
	v_mfma_f32_16x16x32_bf16 v[16:19], v[144:147], v[202:205], v[16:19]
	v_mfma_f32_16x16x32_bf16 v[8:11], v[160:163], v[202:205], v[8:11]
	v_mfma_f32_16x16x32_bf16 v[60:63], v[156:159], v[172:175], v[60:63]
	v_mfma_f32_16x16x32_bf16 v[56:59], v[164:167], v[172:175], v[56:59]
	v_mfma_f32_16x16x32_bf16 v[48:51], v[156:159], v[190:193], v[48:51]
	v_mfma_f32_16x16x32_bf16 v[40:43], v[164:167], v[190:193], v[40:43]
	v_mfma_f32_16x16x32_bf16 v[32:35], v[156:159], v[198:201], v[32:35]
	v_mfma_f32_16x16x32_bf16 v[24:27], v[164:167], v[198:201], v[24:27]
	v_mfma_f32_16x16x32_bf16 v[16:19], v[156:159], v[206:209], v[16:19]
	v_mfma_f32_16x16x32_bf16 v[8:11], v[164:167], v[206:209], v[8:11]
	v_mfma_f32_16x16x32_bf16 v[52:55], v[210:213], v[168:171], v[52:55]
	v_mfma_f32_16x16x32_bf16 v[44:47], v[218:221], v[168:171], v[44:47]
	v_mfma_f32_16x16x32_bf16 v[36:39], v[210:213], v[182:185], v[36:39]
	v_mfma_f32_16x16x32_bf16 v[28:31], v[218:221], v[182:185], v[28:31]
	v_mfma_f32_16x16x32_bf16 v[20:23], v[210:213], v[194:197], v[20:23]
	v_mfma_f32_16x16x32_bf16 v[12:15], v[218:221], v[194:197], v[12:15]
	v_mfma_f32_16x16x32_bf16 v[4:7], v[210:213], v[202:205], v[4:7]
	v_mfma_f32_16x16x32_bf16 v[0:3], v[218:221], v[202:205], v[0:3]
	v_mfma_f32_16x16x32_bf16 v[52:55], v[214:217], v[172:175], v[52:55]
	v_mfma_f32_16x16x32_bf16 v[44:47], v[222:225], v[172:175], v[44:47]
	v_mfma_f32_16x16x32_bf16 v[36:39], v[214:217], v[190:193], v[36:39]
	v_mfma_f32_16x16x32_bf16 v[28:31], v[222:225], v[190:193], v[28:31]
	v_mfma_f32_16x16x32_bf16 v[20:23], v[214:217], v[198:201], v[20:23]
	v_mfma_f32_16x16x32_bf16 v[12:15], v[222:225], v[198:201], v[12:15]
	v_mfma_f32_16x16x32_bf16 v[4:7], v[214:217], v[206:209], v[4:7]
	v_mfma_f32_16x16x32_bf16 v[0:3], v[222:225], v[206:209], v[0:3]
	s_barrier
; #define PG8_STAGE(bufoff, gbase, voff) do { _Pragma("unroll") for (int _i = 0; _i < 2; ++_i) \
;         __builtin_amdgcn_global_load_lds((const unsigned*)((const char*)(gbase) + (voff)[_i]), (PG8_LAS unsigned*)(lds + (bufoff) + ldsw + _i * 8192), 16, 0, 0); } while (0)
; #define PG8_LDA(dst, b, h) do { _Pragma("unroll") for (int m = 0; m < 4; ++m) _Pragma("unroll") for (int k = 0; k < 2; ++k) dst[m][k] = *(const PG8_LAS bf16x8*)(lds + PG8_SA(b, h) + aoff + m * 2048 + k * 1024); } while (0)
; #define PG8_LDB(dst, b, h) do { _Pragma("unroll") for (int n = 0; n < 2; ++n) _Pragma("unroll") for (int k = 0; k < 2; ++k) dst[n][k] = *(const PG8_LAS bf16x8*)(lds + PG8_SB(b, h) + boff + n * 2048 + k * 1024); } while (0)
; #define PG8_MMA(ai, bj, At, Bt) do { __builtin_amdgcn_s_setprio(1); _Pragma("unroll") for (int m = 0; m < 4; ++m) _Pragma("unroll") for (int n = 0; n < 2; ++n) _Pragma("unroll") for (int k = 0; k < 2; ++k) \
;         acc[ai][bj][m][n] = __builtin_amdgcn_mfma_f32_16x16x32_bf16(Bt[n][k], At[m][k], acc[ai][bj][m][n], 0, 0, 0); __builtin_amdgcn_s_setprio(0); } while (0)
; #define PG8_WAIT_V(n) asm volatile("s_waitcnt vmcnt(" #n ")" ::: "memory")
; #define PG8_WAIT_L(n) asm volatile("s_waitcnt lgkmcnt(" #n ")" ::: "memory")
; #define PG8_BAR __builtin_amdgcn_s_barrier()
; #define PG8_SCHED __builtin_amdgcn_sched_barrier(0)
; template <class Epi, class Sched>
; __device__ __forceinline__ void gemm_phase(PG8_LAS unsigned char* lds, const Gemm g, const Sched& S, const Epi& E) {
;     ...
;             PG8_LDB(B0, 1, 0); PG8_SCHED; PG8_LDA(At, 1, 0); PG8_STAGE(PG8_SA(0, 1), a2 + hstep, voffA);
;             PG8_WAIT_L(8); PG8_BAR; PG8_WAIT_L(0); PG8_MMA(0, 0, At, B0); PG8_BAR; PG8_SCHED;
;             PG8_LDB(B1, 1, 1); PG8_STAGE(PG8_SB(1, 0), b3, voffB);
;             PG8_BAR; PG8_WAIT_L(0); PG8_MMA(0, 1, At, B1); PG8_BAR;
;             PG8_LDA(At, 1, 1); PG8_STAGE(PG8_SA(1, 0), a3, voffA);
;             PG8_BAR; PG8_WAIT_L(0); PG8_MMA(1, 0, At, B0); PG8_BAR; PG8_SCHED;
;             PG8_STAGE(PG8_SB(1, 1), b3 + hstep, voffB);
;             PG8_WAIT_V(6); PG8_BAR; PG8_MMA(1, 1, At, B1); PG8_BAR;
	s_add_i32 s48, 0, 0x18000
	v_add_u32_e32 v164, s48, v151
	ds_read_b128 v[144:147], v164
	ds_read_b128 v[156:159], v164 offset:1024
	ds_read_b128 v[160:163], v164 offset:2048
	ds_read_b128 v[164:167], v164 offset:3072
	s_add_u32 s22, s22, 0x40000
	s_addc_u32 s23, s23, 0
	s_mov_b32 m0, s31
	ds_read_b128 v[168:171], v154 offset:32768
	ds_read_b128 v[172:175], v154 offset:33792
	ds_read_b128 v[182:185], v154 offset:34816
	ds_read_b128 v[190:193], v154 offset:35840
	ds_read_b128 v[194:197], v154 offset:36864
	ds_read_b128 v[198:201], v154 offset:37888
	ds_read_b128 v[202:205], v154 offset:38912
	ds_read_b128 v[206:209], v154 offset:39936
	global_load_lds_dwordx4 v128, s[22:23]
	s_nop 1
	s_mov_b32 m0, s34
	s_nop 0
	global_load_lds_dwordx4 v132, s[22:23]
	s_add_i32 s22, 0, 0x1c000
	v_add_u32_e32 v179, s22, v151
	s_waitcnt lgkmcnt(8)
	ds_read_b128 v[210:213], v179
	ds_read_b128 v[214:217], v179 offset:1024
	ds_read_b128 v[218:221], v179 offset:2048
	ds_read_b128 v[222:225], v179 offset:3072
	s_waitcnt vmcnt(8) lgkmcnt(0)
	s_barrier
	v_mfma_f32_16x16x32_bf16 v[124:127], v[144:147], v[168:171], v[124:127]
	v_mfma_f32_16x16x32_bf16 v[120:123], v[160:163], v[168:171], v[120:123]
	v_mfma_f32_16x16x32_bf16 v[112:115], v[144:147], v[182:185], v[112:115]
	v_mfma_f32_16x16x32_bf16 v[104:107], v[160:163], v[182:185], v[104:107]
	v_mfma_f32_16x16x32_bf16 v[96:99], v[144:147], v[194:197], v[96:99]
	v_mfma_f32_16x16x32_bf16 v[88:91], v[160:163], v[194:197], v[88:91]
	v_mfma_f32_16x16x32_bf16 v[80:83], v[144:147], v[202:205], v[80:83]
	v_mfma_f32_16x16x32_bf16 v[72:75], v[160:163], v[202:205], v[72:75]
	v_mfma_f32_16x16x32_bf16 v[124:127], v[156:159], v[172:175], v[124:127]
	v_mfma_f32_16x16x32_bf16 v[120:123], v[164:167], v[172:175], v[120:123]
	v_mfma_f32_16x16x32_bf16 v[112:115], v[156:159], v[190:193], v[112:115]
	v_mfma_f32_16x16x32_bf16 v[104:107], v[164:167], v[190:193], v[104:107]
	v_mfma_f32_16x16x32_bf16 v[96:99], v[156:159], v[198:201], v[96:99]
	v_mfma_f32_16x16x32_bf16 v[88:91], v[164:167], v[198:201], v[88:91]
	v_mfma_f32_16x16x32_bf16 v[80:83], v[156:159], v[206:209], v[80:83]
	v_mfma_f32_16x16x32_bf16 v[72:75], v[164:167], v[206:209], v[72:75]
	v_mfma_f32_16x16x32_bf16 v[116:119], v[210:213], v[168:171], v[116:119]
	v_mfma_f32_16x16x32_bf16 v[108:111], v[218:221], v[168:171], v[108:111]
	v_mfma_f32_16x16x32_bf16 v[100:103], v[210:213], v[182:185], v[100:103]
	v_mfma_f32_16x16x32_bf16 v[92:95], v[218:221], v[182:185], v[92:95]
	v_mfma_f32_16x16x32_bf16 v[84:87], v[210:213], v[194:197], v[84:87]
	v_mfma_f32_16x16x32_bf16 v[76:79], v[218:221], v[194:197], v[76:79]
	v_mfma_f32_16x16x32_bf16 v[68:71], v[210:213], v[202:205], v[68:71]
	v_mfma_f32_16x16x32_bf16 v[64:67], v[218:221], v[202:205], v[64:67]
	v_mfma_f32_16x16x32_bf16 v[116:119], v[214:217], v[172:175], v[116:119]
	v_mfma_f32_16x16x32_bf16 v[108:111], v[222:225], v[172:175], v[108:111]
	v_mfma_f32_16x16x32_bf16 v[100:103], v[214:217], v[190:193], v[100:103]
	v_mfma_f32_16x16x32_bf16 v[92:95], v[222:225], v[190:193], v[92:95]
	v_mfma_f32_16x16x32_bf16 v[84:87], v[214:217], v[198:201], v[84:87]
	v_mfma_f32_16x16x32_bf16 v[76:79], v[222:225], v[198:201], v[76:79]
	v_mfma_f32_16x16x32_bf16 v[68:71], v[214:217], v[206:209], v[68:71]
	v_mfma_f32_16x16x32_bf16 v[64:67], v[222:225], v[206:209], v[64:67]
	s_barrier
	ds_read_b128 v[168:171], v154 offset:49152
	ds_read_b128 v[172:175], v154 offset:50176
	ds_read_b128 v[182:185], v154 offset:51200
	ds_read_b128 v[190:193], v154 offset:52224
	ds_read_b128 v[194:197], v154 offset:53248
	ds_read_b128 v[198:201], v154 offset:54272
	ds_read_b128 v[202:205], v154 offset:55296
	ds_read_b128 v[206:209], v154 offset:56320
	s_add_i32 s23, s48, s29
	s_mov_b32 m0, s23
	s_nop 0
	global_load_lds_dwordx4 v130, s[98:99]
	s_nop 1
	s_add_i32 m0, s23, 0x2000
	s_nop 0
	global_load_lds_dwordx4 v134, s[98:99]
	s_nop 1
	s_mov_b32 m0, s36
	s_nop 0
	global_load_lds_dwordx4 v128, s[100:101]
	s_nop 1
	s_mov_b32 m0, s37
	s_nop 0
	global_load_lds_dwordx4 v132, s[100:101]
	s_add_u32 s20, s20, 0x40080
	s_addc_u32 s21, s21, 0
	s_add_i32 s22, s22, s29
	s_mov_b32 m0, s22
	s_nop 0
	global_load_lds_dwordx4 v130, s[20:21]
	s_nop 1
	s_add_i32 m0, s22, 0x2000
	s_nop 0
	global_load_lds_dwordx4 v134, s[20:21]
	s_waitcnt vmcnt(8) lgkmcnt(0)
	s_barrier
	v_mfma_f32_16x16x32_bf16 v[60:63], v[144:147], v[168:171], v[60:63]
	v_mfma_f32_16x16x32_bf16 v[56:59], v[160:163], v[168:171], v[56:59]
	v_mfma_f32_16x16x32_bf16 v[48:51], v[144:147], v[182:185], v[48:51]
	v_mfma_f32_16x16x32_bf16 v[40:43], v[160:163], v[182:185], v[40:43]
	v_mfma_f32_16x16x32_bf16 v[32:35], v[144:147], v[194:197], v[32:35]
	v_mfma_f32_16x16x32_bf16 v[24:27], v[160:163], v[194:197], v[24:27]
	v_mfma_f32_16x16x32_bf16 v[16:19], v[144:147], v[202:205], v[16:19]
	v_mfma_f32_16x16x32_bf16 v[8:11], v[160:163], v[202:205], v[8:11]
	v_mfma_f32_16x16x32_bf16 v[60:63], v[156:159], v[172:175], v[60:63]
	v_mfma_f32_16x16x32_bf16 v[56:59], v[164:167], v[172:175], v[56:59]
	v_mfma_f32_16x16x32_bf16 v[48:51], v[156:159], v[190:193], v[48:51]
	v_mfma_f32_16x16x32_bf16 v[40:43], v[164:167], v[190:193], v[40:43]
	v_mfma_f32_16x16x32_bf16 v[32:35], v[156:159], v[198:201], v[32:35]
	v_mfma_f32_16x16x32_bf16 v[24:27], v[164:167], v[198:201], v[24:27]
	v_mfma_f32_16x16x32_bf16 v[16:19], v[156:159], v[206:209], v[16:19]
	v_mfma_f32_16x16x32_bf16 v[8:11], v[164:167], v[206:209], v[8:11]
	v_mfma_f32_16x16x32_bf16 v[52:55], v[210:213], v[168:171], v[52:55]
	v_mfma_f32_16x16x32_bf16 v[44:47], v[218:221], v[168:171], v[44:47]
	v_mfma_f32_16x16x32_bf16 v[36:39], v[210:213], v[182:185], v[36:39]
	v_mfma_f32_16x16x32_bf16 v[28:31], v[218:221], v[182:185], v[28:31]
	v_mfma_f32_16x16x32_bf16 v[20:23], v[210:213], v[194:197], v[20:23]
	v_mfma_f32_16x16x32_bf16 v[12:15], v[218:221], v[194:197], v[12:15]
	v_mfma_f32_16x16x32_bf16 v[4:7], v[210:213], v[202:205], v[4:7]
	v_mfma_f32_16x16x32_bf16 v[0:3], v[218:221], v[202:205], v[0:3]
	v_mfma_f32_16x16x32_bf16 v[52:55], v[214:217], v[172:175], v[52:55]
	v_mfma_f32_16x16x32_bf16 v[44:47], v[222:225], v[172:175], v[44:47]
	v_mfma_f32_16x16x32_bf16 v[36:39], v[214:217], v[190:193], v[36:39]
	v_mfma_f32_16x16x32_bf16 v[28:31], v[222:225], v[190:193], v[28:31]
	v_mfma_f32_16x16x32_bf16 v[20:23], v[214:217], v[198:201], v[20:23]
	v_mfma_f32_16x16x32_bf16 v[12:15], v[222:225], v[198:201], v[12:15]
	v_mfma_f32_16x16x32_bf16 v[4:7], v[214:217], v[206:209], v[4:7]
	v_mfma_f32_16x16x32_bf16 v[0:3], v[222:225], v[206:209], v[0:3]
	s_barrier
; __device__ __forceinline__ float bf_lo(unsigned u) { return __uint_as_float(u << 16); }
; __device__ __forceinline__ float bf_hi(unsigned u) { return __uint_as_float(u & 0xffff0000u); }
; #define PG8_MMA(ai, bj, At, Bt) do { __builtin_amdgcn_s_setprio(1); _Pragma("unroll") for (int m = 0; m < 4; ++m) _Pragma("unroll") for (int n = 0; n < 2; ++n) _Pragma("unroll") for (int k = 0; k < 2; ++k) \
;         acc[ai][bj][m][n] = __builtin_amdgcn_mfma_f32_16x16x32_bf16(Bt[n][k], At[m][k], acc[ai][bj][m][n], 0, 0, 0); __builtin_amdgcn_s_setprio(0); } while (0)
; #define PG8_WAIT_V(n) asm volatile("s_waitcnt vmcnt(" #n ")" ::: "memory")
; #define PG8_BAR __builtin_amdgcn_s_barrier()
;     __device__ __forceinline__ void operator()(const f32x4 (&acc)[2][2][4][2], const Unit& u, int wr, int wc, int fr, int fq) const {
;     ...
;             for (int m = 0; m < 4; ++m) { const size_t r = (size_t)(row0 + ai * HALF + m * 16); bf16_t* rowp = O + r * ldc + col0; const bf16_t* gp = G + r * ldg + col0;
; #pragma unroll
;                 for (int bj = 0; bj < 2; ++bj) { const u32x4 gw = *(const u32x4*)(gp + bj * HALF);
;                     f32x4 v0 = acc[ai][bj][m][0], v1 = acc[ai][bj][m][1];
;                     v0[0] *= bf_lo(gw.x); v0[1] *= bf_hi(gw.x); v0[2] *= bf_lo(gw.y); v0[3] *= bf_hi(gw.y);
;                     v1[0] *= bf_lo(gw.z); v1[1] *= bf_hi(gw.z); v1[2] *= bf_lo(gw.w); v1[3] *= bf_hi(gw.w);
; template <class Epi, class Sched>
; __device__ __forceinline__ void gemm_phase(PG8_LAS unsigned char* lds, const Gemm g, const Sched& S, const Epi& E) {
;     ...
;             PG8_WAIT_V(6); PG8_BAR; PG8_MMA(1, 1, At, B1); PG8_BAR;
;         }
	s_add_i32 s47, s47, 2
	s_add_u32 s18, s18, 0x100
	s_addc_u32 s19, s19, 0
	s_add_u32 s45, s45, 0x100
	s_addc_u32 s46, s46, 0
	s_cmp_gt_u32 s47, 13
	s_cbranch_scc0 .LBB0_991
	v_lshl_or_b32 v144, s42, 8, v152
	v_lshl_add_u32 v146, s16, 8, v150
	v_ashrrev_i32_e32 v145, 31, v144
	v_mov_b64_e32 v[148:149], s[4:5]
	v_lshlrev_b64 v[144:145], 1, v[144:145]
	v_mad_i64_i32 v[156:157], s[18:19], v146, s41, v[148:149]
	v_lshl_add_u64 v[160:161], v[156:157], 0, v[144:145]
	global_load_dwordx4 v[166:169], v[160:161], off offset:3072
	global_load_dwordx4 v[170:173], v[160:161], off offset:3328
	s_mul_i32 s98, s41, 16
	s_mov_b32 s99, 0
	v_lshl_add_u64 v[224:225], v[160:161], 0, s[98:99]
	global_load_dwordx4 v[182:185], v[224:225], off offset:3072
	global_load_dwordx4 v[190:193], v[224:225], off offset:3328
	s_mul_i32 s98, s41, 32
	s_mov_b32 s99, 0
	v_lshl_add_u64 v[174:175], v[160:161], 0, s[98:99]
	global_load_dwordx4 v[194:197], v[174:175], off offset:3072
	global_load_dwordx4 v[198:201], v[174:175], off offset:3328
	s_mul_i32 s98, s41, 48
	s_mov_b32 s99, 0
	v_lshl_add_u64 v[224:225], v[160:161], 0, s[98:99]
	global_load_dwordx4 v[202:205], v[224:225], off offset:3072
	global_load_dwordx4 v[206:209], v[224:225], off offset:3328
	s_mul_i32 s98, s41, 128
	s_mov_b32 s99, 0
	v_lshl_add_u64 v[174:175], v[160:161], 0, s[98:99]
	global_load_dwordx4 v[210:213], v[174:175], off offset:3072
	global_load_dwordx4 v[214:217], v[174:175], off offset:3328
	s_mul_i32 s98, s41, 144
	s_mov_b32 s99, 0
	v_lshl_add_u64 v[218:219], v[160:161], 0, s[98:99]
	s_mul_i32 s98, s41, 160
	s_mov_b32 s99, 0
	v_lshl_add_u64 v[220:221], v[160:161], 0, s[98:99]
	s_mul_i32 s98, s41, 176
	s_mov_b32 s99, 0
	v_lshl_add_u64 v[222:223], v[160:161], 0, s[98:99]
	s_and_b64 vcc, exec, s[2:3]
	s_mov_b32 s42, s8
	s_mov_b32 s16, s10
	s_mov_b64 s[20:21], s[14:15]
	s_waitcnt vmcnt(9)
	v_mov_b32_e32 v156, v166
	v_mov_b32_e32 v157, v167
	v_mov_b32_e32 v158, v168
	v_mov_b32_e32 v159, v169
	global_load_dwordx4 v[166:169], v[218:219], off offset:3072
	v_lshlrev_b32_e32 v147, 16, v156
	v_and_b32_e32 v156, 0xffff0000, v156
	v_lshlrev_b32_e32 v162, 16, v157
	v_and_b32_e32 v157, 0xffff0000, v157
	v_lshlrev_b32_e32 v164, 16, v159
	v_and_b32_e32 v159, 0xffff0000, v159
	v_lshlrev_b32_e32 v163, 16, v158
	v_and_b32_e32 v158, 0xffff0000, v158
	v_mul_f32_e32 v124, v124, v147
	v_mul_f32_e32 v125, v125, v156
	v_mul_f32_e32 v126, v126, v162
	v_mul_f32_e32 v127, v127, v157
	v_mul_f32_e32 v123, v123, v159
	v_mul_f32_e32 v147, v120, v163
	v_mul_f32_e32 v156, v121, v158
	v_mul_f32_e32 v157, v122, v164
	v_cvt_pk_bf16_f32 v120, v124, v125
	v_cvt_pk_bf16_f32 v121, v126, v127
	v_cvt_pk_bf16_f32 v122, v147, v156
	v_cvt_pk_bf16_f32 v123, v157, v123
	v_ashrrev_i32_e32 v147, 31, v146
	v_lshlrev_b64 v[158:159], 11, v[146:147]
	v_lshl_add_u64 v[158:159], s[0:1], 0, v[158:159]
	v_or_b32_e32 v156, 16, v146
	v_lshl_add_u64 v[158:159], v[158:159], 0, v[144:145]
	v_mad_i64_i32 v[160:161], s[18:19], v156, s41, v[148:149]
	global_store_dwordx4 v[158:159], v[120:123], off
	v_lshl_add_u64 v[160:161], v[160:161], 0, v[144:145]
	v_ashrrev_i32_e32 v157, 31, v156
	s_waitcnt vmcnt(10)
	v_mov_b32_e32 v124, v170
	v_mov_b32_e32 v125, v171
	v_mov_b32_e32 v126, v172
	v_mov_b32_e32 v127, v173
	global_load_dwordx4 v[170:173], v[218:219], off offset:3328
	v_lshlrev_b32_e32 v120, 16, v124
	v_and_b32_e32 v121, 0xffff0000, v124
	v_lshlrev_b32_e32 v122, 16, v125
	v_and_b32_e32 v123, 0xffff0000, v125
	v_lshlrev_b32_e32 v124, 16, v126
	v_and_b32_e32 v125, 0xffff0000, v126
	v_lshlrev_b32_e32 v126, 16, v127
	v_and_b32_e32 v127, 0xffff0000, v127
	v_mul_f32_e32 v116, v116, v120
	v_mul_f32_e32 v117, v117, v121
	v_mul_f32_e32 v118, v118, v122
	v_mul_f32_e32 v119, v119, v123
	v_mul_f32_e32 v111, v111, v127
	v_mul_f32_e32 v120, v108, v124
	v_mul_f32_e32 v121, v109, v125
	v_mul_f32_e32 v122, v110, v126
	v_cvt_pk_bf16_f32 v108, v116, v117
	v_cvt_pk_bf16_f32 v109, v118, v119
	v_cvt_pk_bf16_f32 v110, v120, v121
	v_cvt_pk_bf16_f32 v111, v122, v111
	s_nop 0
	global_store_dwordx4 v[158:159], v[108:111], off offset:256
	s_waitcnt vmcnt(11)
	v_mov_b32_e32 v116, v182
	v_mov_b32_e32 v117, v183
	v_mov_b32_e32 v118, v184
	v_mov_b32_e32 v119, v185
	global_load_dwordx4 v[182:185], v[220:221], off offset:3072
	s_nop 0
	v_lshlrev_b32_e32 v108, 16, v116
	v_and_b32_e32 v109, 0xffff0000, v116
	v_lshlrev_b32_e32 v110, 16, v117
	v_and_b32_e32 v111, 0xffff0000, v117
	v_lshlrev_b32_e32 v116, 16, v118
	v_and_b32_e32 v117, 0xffff0000, v118
	v_lshlrev_b32_e32 v118, 16, v119
	v_and_b32_e32 v119, 0xffff0000, v119
	v_mul_f32_e32 v108, v112, v108
	v_mul_f32_e32 v109, v113, v109
	v_mul_f32_e32 v110, v114, v110
	v_mul_f32_e32 v111, v115, v111
	v_mul_f32_e32 v107, v107, v119
	v_mul_f32_e32 v112, v104, v116
	v_mul_f32_e32 v113, v105, v117
	v_mul_f32_e32 v114, v106, v118
	v_cvt_pk_bf16_f32 v104, v108, v109
	v_cvt_pk_bf16_f32 v105, v110, v111
	v_cvt_pk_bf16_f32 v106, v112, v113
	v_cvt_pk_bf16_f32 v107, v114, v107
	v_lshlrev_b64 v[116:117], 11, v[156:157]
	v_lshl_add_u64 v[116:117], s[0:1], 0, v[116:117]
	v_or_b32_e32 v112, 32, v146
	v_lshl_add_u64 v[116:117], v[116:117], 0, v[144:145]
	v_mad_i64_i32 v[114:115], s[18:19], v112, s41, v[148:149]
	global_store_dwordx4 v[116:117], v[104:107], off
	v_lshl_add_u64 v[114:115], v[114:115], 0, v[144:145]
	v_ashrrev_i32_e32 v113, 31, v112
	s_waitcnt vmcnt(12)
; __device__ __forceinline__ unsigned cvt_pk_bf16(float lo, float hi) { unsigned r; asm volatile("v_cvt_pk_bf16_f32 %0, %1, %2" : "=v"(r) : "v"(lo), "v"(hi)); return r; }
; __device__ __forceinline__ float bf_lo(unsigned u) { return __uint_as_float(u << 16); }
; __device__ __forceinline__ float bf_hi(unsigned u) { return __uint_as_float(u & 0xffff0000u); }
;     __device__ __forceinline__ void operator()(const f32x4 (&acc)[2][2][4][2], const Unit& u, int wr, int wc, int fr, int fq) const {
;     ...
;             for (int m = 0; m < 4; ++m) { const size_t r = (size_t)(row0 + ai * HALF + m * 16); bf16_t* rowp = O + r * ldc + col0; const bf16_t* gp = G + r * ldg + col0;
; #pragma unroll
;                 for (int bj = 0; bj < 2; ++bj) { const u32x4 gw = *(const u32x4*)(gp + bj * HALF);
;                     f32x4 v0 = acc[ai][bj][m][0], v1 = acc[ai][bj][m][1];
;                     v0[0] *= bf_lo(gw.x); v0[1] *= bf_hi(gw.x); v0[2] *= bf_lo(gw.y); v0[3] *= bf_hi(gw.y);
;                     v1[0] *= bf_lo(gw.z); v1[1] *= bf_hi(gw.z); v1[2] *= bf_lo(gw.w); v1[3] *= bf_hi(gw.w);
;                     if (ACCUM) { const u32x4 pw = *(const u32x4*)(rowp + bj * HALF);
;                         v0[0] += bf_lo(pw.x); v0[1] += bf_hi(pw.x); v0[2] += bf_lo(pw.y); v0[3] += bf_hi(pw.y);
;                         v1[0] += bf_lo(pw.z); v1[1] += bf_hi(pw.z); v1[2] += bf_lo(pw.w); v1[3] += bf_hi(pw.w); }
;                     u32x4 w; w.x = cvt_pk_bf16(v0[0], v0[1]); w.y = cvt_pk_bf16(v0[2], v0[3]); w.z = cvt_pk_bf16(v1[0], v1[1]); w.w = cvt_pk_bf16(v1[2], v1[3]);
;                     *(u32x4*)(rowp + bj * HALF) = w; } }
	v_mov_b32_e32 v108, v190
	v_mov_b32_e32 v109, v191
	v_mov_b32_e32 v110, v192
	v_mov_b32_e32 v111, v193
	global_load_dwordx4 v[190:193], v[220:221], off offset:3328
	v_lshlrev_b32_e32 v104, 16, v108
	v_and_b32_e32 v105, 0xffff0000, v108
	v_lshlrev_b32_e32 v106, 16, v109
	v_and_b32_e32 v107, 0xffff0000, v109
	v_lshlrev_b32_e32 v108, 16, v110
	v_and_b32_e32 v109, 0xffff0000, v110
	v_lshlrev_b32_e32 v110, 16, v111
	v_and_b32_e32 v111, 0xffff0000, v111
	v_mul_f32_e32 v100, v100, v104
	v_mul_f32_e32 v101, v101, v105
	v_mul_f32_e32 v102, v102, v106
	v_mul_f32_e32 v103, v103, v107
	v_mul_f32_e32 v95, v95, v111
	v_mul_f32_e32 v104, v92, v108
	v_mul_f32_e32 v105, v93, v109
	v_mul_f32_e32 v106, v94, v110
	v_cvt_pk_bf16_f32 v92, v100, v101
	v_cvt_pk_bf16_f32 v93, v102, v103
	v_cvt_pk_bf16_f32 v94, v104, v105
	v_cvt_pk_bf16_f32 v95, v106, v95
	s_nop 0
	global_store_dwordx4 v[116:117], v[92:95], off offset:256
	s_waitcnt vmcnt(13)
	v_mov_b32_e32 v100, v194
	v_mov_b32_e32 v101, v195
	v_mov_b32_e32 v102, v196
	v_mov_b32_e32 v103, v197
	global_load_dwordx4 v[194:197], v[222:223], off offset:3072
	s_nop 0
	v_lshlrev_b32_e32 v92, 16, v100
	v_and_b32_e32 v93, 0xffff0000, v100
	v_lshlrev_b32_e32 v94, 16, v101
	v_and_b32_e32 v95, 0xffff0000, v101
	v_lshlrev_b32_e32 v100, 16, v102
	v_and_b32_e32 v101, 0xffff0000, v102
	v_lshlrev_b32_e32 v102, 16, v103
	v_and_b32_e32 v103, 0xffff0000, v103
	v_mul_f32_e32 v92, v96, v92
	v_mul_f32_e32 v93, v97, v93
	v_mul_f32_e32 v94, v98, v94
	v_mul_f32_e32 v95, v99, v95
	v_mul_f32_e32 v91, v91, v103
	v_mul_f32_e32 v96, v88, v100
	v_mul_f32_e32 v97, v89, v101
	v_mul_f32_e32 v98, v90, v102
	v_cvt_pk_bf16_f32 v88, v92, v93
	v_cvt_pk_bf16_f32 v89, v94, v95
	v_cvt_pk_bf16_f32 v90, v96, v97
	v_cvt_pk_bf16_f32 v91, v98, v91
	v_lshlrev_b64 v[100:101], 11, v[112:113]
	v_lshl_add_u64 v[100:101], s[0:1], 0, v[100:101]
	v_or_b32_e32 v96, 48, v146
	v_lshl_add_u64 v[100:101], v[100:101], 0, v[144:145]
	v_mad_i64_i32 v[98:99], s[18:19], v96, s41, v[148:149]
	global_store_dwordx4 v[100:101], v[88:91], off
	v_lshl_add_u64 v[98:99], v[98:99], 0, v[144:145]
	v_ashrrev_i32_e32 v97, 31, v96
	s_waitcnt vmcnt(14)
	v_mov_b32_e32 v92, v198
	v_mov_b32_e32 v93, v199
	v_mov_b32_e32 v94, v200
	v_mov_b32_e32 v95, v201
	global_load_dwordx4 v[198:201], v[222:223], off offset:3328
	v_lshlrev_b32_e32 v88, 16, v92
	v_and_b32_e32 v89, 0xffff0000, v92
	v_lshlrev_b32_e32 v90, 16, v93
	v_and_b32_e32 v91, 0xffff0000, v93
	v_lshlrev_b32_e32 v92, 16, v94
	v_and_b32_e32 v93, 0xffff0000, v94
	v_lshlrev_b32_e32 v94, 16, v95
	v_and_b32_e32 v95, 0xffff0000, v95
	v_mul_f32_e32 v84, v84, v88
	v_mul_f32_e32 v85, v85, v89
	v_mul_f32_e32 v86, v86, v90
	v_mul_f32_e32 v87, v87, v91
	v_mul_f32_e32 v79, v79, v95
	v_mul_f32_e32 v88, v76, v92
	v_mul_f32_e32 v89, v77, v93
	v_mul_f32_e32 v90, v78, v94
	v_cvt_pk_bf16_f32 v76, v84, v85
	v_cvt_pk_bf16_f32 v77, v86, v87
	v_cvt_pk_bf16_f32 v78, v88, v89
	v_cvt_pk_bf16_f32 v79, v90, v79
	s_nop 0
	global_store_dwordx4 v[100:101], v[76:79], off offset:256
	s_waitcnt vmcnt(15)
	v_mov_b32_e32 v84, v202
	v_mov_b32_e32 v85, v203
	v_mov_b32_e32 v86, v204
	v_mov_b32_e32 v87, v205
	s_nop 0
	v_lshlrev_b32_e32 v76, 16, v84
	v_and_b32_e32 v77, 0xffff0000, v84
	v_lshlrev_b32_e32 v78, 16, v85
	v_and_b32_e32 v79, 0xffff0000, v85
	v_lshlrev_b32_e32 v84, 16, v86
	v_and_b32_e32 v85, 0xffff0000, v86
	v_lshlrev_b32_e32 v86, 16, v87
	v_and_b32_e32 v87, 0xffff0000, v87
	v_mul_f32_e32 v76, v80, v76
	v_mul_f32_e32 v77, v81, v77
	v_mul_f32_e32 v78, v82, v78
	v_mul_f32_e32 v79, v83, v79
	v_mul_f32_e32 v75, v75, v87
	v_mul_f32_e32 v80, v72, v84
	v_mul_f32_e32 v81, v73, v85
	v_mul_f32_e32 v82, v74, v86
	v_cvt_pk_bf16_f32 v72, v76, v77
	v_cvt_pk_bf16_f32 v73, v78, v79
	v_cvt_pk_bf16_f32 v74, v80, v81
	v_cvt_pk_bf16_f32 v75, v82, v75
	v_lshlrev_b64 v[84:85], 11, v[96:97]
	v_lshl_add_u64 v[84:85], s[0:1], 0, v[84:85]
	v_add_u32_e32 v80, 0x80, v146
	v_lshl_add_u64 v[84:85], v[84:85], 0, v[144:145]
	v_mad_i64_i32 v[82:83], s[18:19], v80, s41, v[148:149]
	global_store_dwordx4 v[84:85], v[72:75], off
	v_lshl_add_u64 v[82:83], v[82:83], 0, v[144:145]
	v_ashrrev_i32_e32 v81, 31, v80
	s_waitcnt vmcnt(15)
	v_mov_b32_e32 v76, v206
	v_mov_b32_e32 v77, v207
	v_mov_b32_e32 v78, v208
	v_mov_b32_e32 v79, v209
	v_lshlrev_b32_e32 v72, 16, v76
	v_and_b32_e32 v73, 0xffff0000, v76
	v_lshlrev_b32_e32 v74, 16, v77
	v_and_b32_e32 v75, 0xffff0000, v77
	v_lshlrev_b32_e32 v76, 16, v78
	v_and_b32_e32 v77, 0xffff0000, v78
	v_lshlrev_b32_e32 v78, 16, v79
	v_and_b32_e32 v79, 0xffff0000, v79
	v_mul_f32_e32 v68, v68, v72
	v_mul_f32_e32 v69, v69, v73
	v_mul_f32_e32 v70, v70, v74
	v_mul_f32_e32 v71, v71, v75
	v_mul_f32_e32 v67, v67, v79
	v_mul_f32_e32 v72, v64, v76
	v_mul_f32_e32 v73, v65, v77
	v_mul_f32_e32 v74, v66, v78
	v_cvt_pk_bf16_f32 v64, v68, v69
	v_cvt_pk_bf16_f32 v65, v70, v71
	v_cvt_pk_bf16_f32 v66, v72, v73
	v_cvt_pk_bf16_f32 v67, v74, v67
	s_nop 0
	global_store_dwordx4 v[84:85], v[64:67], off offset:256
	s_waitcnt vmcnt(15)
	v_mov_b32_e32 v68, v210
	v_mov_b32_e32 v69, v211
	v_mov_b32_e32 v70, v212
	v_mov_b32_e32 v71, v213
	s_nop 0
	v_lshlrev_b32_e32 v64, 16, v68
	v_and_b32_e32 v65, 0xffff0000, v68
	v_lshlrev_b32_e32 v66, 16, v69
	v_and_b32_e32 v67, 0xffff0000, v69
	v_lshlrev_b32_e32 v68, 16, v70
	v_and_b32_e32 v69, 0xffff0000, v70
	v_lshlrev_b32_e32 v70, 16, v71
	v_and_b32_e32 v71, 0xffff0000, v71
	v_mul_f32_e32 v60, v60, v64
	v_mul_f32_e32 v61, v61, v65
	v_mul_f32_e32 v62, v62, v66
	v_mul_f32_e32 v63, v63, v67
	v_mul_f32_e32 v59, v59, v71
	v_mul_f32_e32 v64, v56, v68
	v_mul_f32_e32 v65, v57, v69
	v_mul_f32_e32 v66, v58, v70
	v_cvt_pk_bf16_f32 v56, v60, v61
	v_cvt_pk_bf16_f32 v57, v62, v63
	v_cvt_pk_bf16_f32 v58, v64, v65
	v_cvt_pk_bf16_f32 v59, v66, v59
	v_lshlrev_b64 v[68:69], 11, v[80:81]
	v_lshl_add_u64 v[68:69], s[0:1], 0, v[68:69]
	v_add_u32_e32 v64, 0x90, v146
	v_lshl_add_u64 v[68:69], v[68:69], 0, v[144:145]
	v_mad_i64_i32 v[66:67], s[18:19], v64, s41, v[148:149]
	global_store_dwordx4 v[68:69], v[56:59], off
	v_lshl_add_u64 v[66:67], v[66:67], 0, v[144:145]
	v_ashrrev_i32_e32 v65, 31, v64
	s_waitcnt vmcnt(15)
; __device__ __forceinline__ unsigned cvt_pk_bf16(float lo, float hi) { unsigned r; asm volatile("v_cvt_pk_bf16_f32 %0, %1, %2" : "=v"(r) : "v"(lo), "v"(hi)); return r; }
; __device__ __forceinline__ float bf_lo(unsigned u) { return __uint_as_float(u << 16); }
; __device__ __forceinline__ float bf_hi(unsigned u) { return __uint_as_float(u & 0xffff0000u); }
; #define PG8_WAIT_V(n) asm volatile("s_waitcnt vmcnt(" #n ")" ::: "memory")
; #define PG8_BAR __builtin_amdgcn_s_barrier()
;     __device__ __forceinline__ void operator()(const f32x4 (&acc)[2][2][4][2], const Unit& u, int wr, int wc, int fr, int fq) const {
;     ...
;             for (int m = 0; m < 4; ++m) { const size_t r = (size_t)(row0 + ai * HALF + m * 16); bf16_t* rowp = O + r * ldc + col0; const bf16_t* gp = G + r * ldg + col0;
; #pragma unroll
;                 for (int bj = 0; bj < 2; ++bj) { const u32x4 gw = *(const u32x4*)(gp + bj * HALF);
;                     f32x4 v0 = acc[ai][bj][m][0], v1 = acc[ai][bj][m][1];
;                     v0[0] *= bf_lo(gw.x); v0[1] *= bf_hi(gw.x); v0[2] *= bf_lo(gw.y); v0[3] *= bf_hi(gw.y);
;                     v1[0] *= bf_lo(gw.z); v1[1] *= bf_hi(gw.z); v1[2] *= bf_lo(gw.w); v1[3] *= bf_hi(gw.w);
;                     if (ACCUM) { const u32x4 pw = *(const u32x4*)(rowp + bj * HALF);
;                         v0[0] += bf_lo(pw.x); v0[1] += bf_hi(pw.x); v0[2] += bf_lo(pw.y); v0[3] += bf_hi(pw.y);
;                         v1[0] += bf_lo(pw.z); v1[1] += bf_hi(pw.z); v1[2] += bf_lo(pw.w); v1[3] += bf_hi(pw.w); }
;                     u32x4 w; w.x = cvt_pk_bf16(v0[0], v0[1]); w.y = cvt_pk_bf16(v0[2], v0[3]); w.z = cvt_pk_bf16(v1[0], v1[1]); w.w = cvt_pk_bf16(v1[2], v1[3]);
;                     *(u32x4*)(rowp + bj * HALF) = w; } }
; template <class Epi, class Sched>
; __device__ __forceinline__ void gemm_phase(PG8_LAS unsigned char* lds, const Gemm g, const Sched& S, const Epi& E) {
;     ...
;         if (!has_next) break;
; #pragma unroll
;         for (int a = 0; a < 2; ++a)
; #pragma unroll
;             for (int b = 0; b < 2; ++b)
; #pragma unroll
;                 for (int m = 0; m < 4; ++m)
; #pragma unroll
;                     for (int n = 0; n < 2; ++n) acc[a][b][m][n] = (f32x4){0.f, 0.f, 0.f, 0.f};
;         cur = nxt; cA = nA; cB = nB; ++ui;
;     }
;     PG8_WAIT_V(0);
;     if (wr == 0) PG8_BAR;
;     PG8_BAR;
	v_mov_b32_e32 v60, v214
	v_mov_b32_e32 v61, v215
	v_mov_b32_e32 v62, v216
	v_mov_b32_e32 v63, v217
	v_lshlrev_b32_e32 v56, 16, v60
	v_and_b32_e32 v57, 0xffff0000, v60
	v_lshlrev_b32_e32 v58, 16, v61
	v_and_b32_e32 v59, 0xffff0000, v61
	v_lshlrev_b32_e32 v60, 16, v62
	v_and_b32_e32 v61, 0xffff0000, v62
	v_lshlrev_b32_e32 v62, 16, v63
	v_and_b32_e32 v63, 0xffff0000, v63
	v_mul_f32_e32 v52, v52, v56
	v_mul_f32_e32 v53, v53, v57
	v_mul_f32_e32 v54, v54, v58
	v_mul_f32_e32 v55, v55, v59
	v_mul_f32_e32 v47, v47, v63
	v_mul_f32_e32 v56, v44, v60
	v_mul_f32_e32 v57, v45, v61
	v_mul_f32_e32 v58, v46, v62
	v_cvt_pk_bf16_f32 v44, v52, v53
	v_cvt_pk_bf16_f32 v45, v54, v55
	v_cvt_pk_bf16_f32 v46, v56, v57
	v_cvt_pk_bf16_f32 v47, v58, v47
	s_nop 0
	global_store_dwordx4 v[68:69], v[44:47], off offset:256
	s_waitcnt vmcnt(15)
	v_mov_b32_e32 v52, v166
	v_mov_b32_e32 v53, v167
	v_mov_b32_e32 v54, v168
	v_mov_b32_e32 v55, v169
	s_nop 0
	v_lshlrev_b32_e32 v44, 16, v52
	v_and_b32_e32 v45, 0xffff0000, v52
	v_lshlrev_b32_e32 v46, 16, v53
	v_and_b32_e32 v47, 0xffff0000, v53
	v_lshlrev_b32_e32 v52, 16, v54
	v_and_b32_e32 v53, 0xffff0000, v54
	v_lshlrev_b32_e32 v54, 16, v55
	v_and_b32_e32 v55, 0xffff0000, v55
	v_mul_f32_e32 v44, v48, v44
	v_mul_f32_e32 v45, v49, v45
	v_mul_f32_e32 v46, v50, v46
	v_mul_f32_e32 v47, v51, v47
	v_mul_f32_e32 v43, v43, v55
	v_mul_f32_e32 v48, v40, v52
	v_mul_f32_e32 v49, v41, v53
	v_mul_f32_e32 v50, v42, v54
	v_cvt_pk_bf16_f32 v40, v44, v45
	v_cvt_pk_bf16_f32 v41, v46, v47
	v_cvt_pk_bf16_f32 v42, v48, v49
	v_cvt_pk_bf16_f32 v43, v50, v43
	v_lshlrev_b64 v[52:53], 11, v[64:65]
	v_lshl_add_u64 v[52:53], s[0:1], 0, v[52:53]
	v_add_u32_e32 v48, 0xa0, v146
	v_lshl_add_u64 v[52:53], v[52:53], 0, v[144:145]
	v_mad_i64_i32 v[50:51], s[18:19], v48, s41, v[148:149]
	global_store_dwordx4 v[52:53], v[40:43], off
	v_lshl_add_u64 v[50:51], v[50:51], 0, v[144:145]
	v_ashrrev_i32_e32 v49, 31, v48
	s_waitcnt vmcnt(14)
	v_mov_b32_e32 v44, v170
	v_mov_b32_e32 v45, v171
	v_mov_b32_e32 v46, v172
	v_mov_b32_e32 v47, v173
	v_lshlrev_b32_e32 v40, 16, v44
	v_and_b32_e32 v41, 0xffff0000, v44
	v_lshlrev_b32_e32 v42, 16, v45
	v_and_b32_e32 v43, 0xffff0000, v45
	v_lshlrev_b32_e32 v44, 16, v46
	v_and_b32_e32 v45, 0xffff0000, v46
	v_lshlrev_b32_e32 v46, 16, v47
	v_and_b32_e32 v47, 0xffff0000, v47
	v_mul_f32_e32 v36, v36, v40
	v_mul_f32_e32 v37, v37, v41
	v_mul_f32_e32 v38, v38, v42
	v_mul_f32_e32 v39, v39, v43
	v_mul_f32_e32 v31, v31, v47
	v_mul_f32_e32 v40, v28, v44
	v_mul_f32_e32 v41, v29, v45
	v_mul_f32_e32 v42, v30, v46
	v_cvt_pk_bf16_f32 v28, v36, v37
	v_cvt_pk_bf16_f32 v29, v38, v39
	v_cvt_pk_bf16_f32 v30, v40, v41
	v_cvt_pk_bf16_f32 v31, v42, v31
	s_nop 0
	global_store_dwordx4 v[52:53], v[28:31], off offset:256
	s_waitcnt vmcnt(13)
	v_mov_b32_e32 v36, v182
	v_mov_b32_e32 v37, v183
	v_mov_b32_e32 v38, v184
	v_mov_b32_e32 v39, v185
	s_nop 0
	v_lshlrev_b32_e32 v28, 16, v36
	v_and_b32_e32 v29, 0xffff0000, v36
	v_lshlrev_b32_e32 v30, 16, v37
	v_and_b32_e32 v31, 0xffff0000, v37
	v_lshlrev_b32_e32 v36, 16, v38
	v_and_b32_e32 v37, 0xffff0000, v38
	v_lshlrev_b32_e32 v38, 16, v39
	v_and_b32_e32 v39, 0xffff0000, v39
	v_mul_f32_e32 v28, v32, v28
	v_mul_f32_e32 v29, v33, v29
	v_mul_f32_e32 v30, v34, v30
	v_mul_f32_e32 v31, v35, v31
	v_mul_f32_e32 v27, v27, v39
	v_mul_f32_e32 v32, v24, v36
	v_mul_f32_e32 v33, v25, v37
	v_mul_f32_e32 v34, v26, v38
	v_cvt_pk_bf16_f32 v24, v28, v29
	v_cvt_pk_bf16_f32 v25, v30, v31
	v_cvt_pk_bf16_f32 v26, v32, v33
	v_cvt_pk_bf16_f32 v27, v34, v27
	v_lshlrev_b64 v[36:37], 11, v[48:49]
	v_lshl_add_u64 v[36:37], s[0:1], 0, v[36:37]
	v_add_u32_e32 v32, 0xb0, v146
	v_lshl_add_u64 v[36:37], v[36:37], 0, v[144:145]
	v_mad_i64_i32 v[34:35], s[18:19], v32, s41, v[148:149]
	global_store_dwordx4 v[36:37], v[24:27], off
	v_lshl_add_u64 v[34:35], v[34:35], 0, v[144:145]
	v_ashrrev_i32_e32 v33, 31, v32
	s_mov_b64 s[18:19], s[12:13]
	s_waitcnt vmcnt(12)
	v_mov_b32_e32 v28, v190
	v_mov_b32_e32 v29, v191
	v_mov_b32_e32 v30, v192
	v_mov_b32_e32 v31, v193
	v_lshlrev_b32_e32 v24, 16, v28
	v_and_b32_e32 v25, 0xffff0000, v28
	v_lshlrev_b32_e32 v26, 16, v29
	v_and_b32_e32 v27, 0xffff0000, v29
	v_lshlrev_b32_e32 v28, 16, v30
	v_and_b32_e32 v29, 0xffff0000, v30
	v_lshlrev_b32_e32 v30, 16, v31
	v_and_b32_e32 v31, 0xffff0000, v31
	v_mul_f32_e32 v20, v20, v24
	v_mul_f32_e32 v21, v21, v25
	v_mul_f32_e32 v22, v22, v26
	v_mul_f32_e32 v23, v23, v27
	v_mul_f32_e32 v15, v15, v31
	v_mul_f32_e32 v24, v12, v28
	v_mul_f32_e32 v25, v13, v29
	v_mul_f32_e32 v26, v14, v30
	v_cvt_pk_bf16_f32 v12, v20, v21
	v_cvt_pk_bf16_f32 v13, v22, v23
	v_cvt_pk_bf16_f32 v14, v24, v25
	v_cvt_pk_bf16_f32 v15, v26, v15
	s_nop 0
	global_store_dwordx4 v[36:37], v[12:15], off offset:256
	s_waitcnt vmcnt(11)
	v_mov_b32_e32 v20, v194
	v_mov_b32_e32 v21, v195
	v_mov_b32_e32 v22, v196
	v_mov_b32_e32 v23, v197
	s_nop 0
	v_lshlrev_b32_e32 v12, 16, v20
	v_and_b32_e32 v13, 0xffff0000, v20
	v_lshlrev_b32_e32 v14, 16, v21
	v_and_b32_e32 v15, 0xffff0000, v21
	v_lshlrev_b32_e32 v20, 16, v22
	v_and_b32_e32 v21, 0xffff0000, v22
	v_lshlrev_b32_e32 v22, 16, v23
	v_and_b32_e32 v23, 0xffff0000, v23
	v_mul_f32_e32 v12, v16, v12
	v_mul_f32_e32 v13, v17, v13
	v_mul_f32_e32 v14, v18, v14
	v_mul_f32_e32 v15, v19, v15
	v_mul_f32_e32 v11, v11, v23
	v_mul_f32_e32 v16, v8, v20
	v_mul_f32_e32 v17, v9, v21
	v_mul_f32_e32 v18, v10, v22
	v_cvt_pk_bf16_f32 v8, v12, v13
	v_cvt_pk_bf16_f32 v9, v14, v15
	v_cvt_pk_bf16_f32 v10, v16, v17
	v_cvt_pk_bf16_f32 v11, v18, v11
	v_lshlrev_b64 v[16:17], 11, v[32:33]
	v_lshl_add_u64 v[16:17], s[0:1], 0, v[16:17]
	v_lshl_add_u64 v[16:17], v[16:17], 0, v[144:145]
	global_store_dwordx4 v[16:17], v[8:11], off
	s_waitcnt vmcnt(10)
	v_mov_b32_e32 v12, v198
	v_mov_b32_e32 v13, v199
	v_mov_b32_e32 v14, v200
	v_mov_b32_e32 v15, v201
	s_nop 0
	v_lshlrev_b32_e32 v8, 16, v12
	v_and_b32_e32 v9, 0xffff0000, v12
	v_lshlrev_b32_e32 v10, 16, v13
	v_and_b32_e32 v11, 0xffff0000, v13
	v_lshlrev_b32_e32 v12, 16, v14
	v_and_b32_e32 v13, 0xffff0000, v14
	v_lshlrev_b32_e32 v14, 16, v15
	v_and_b32_e32 v15, 0xffff0000, v15
	v_mul_f32_e32 v3, v3, v15
	v_mul_f32_e32 v4, v4, v8
	v_mul_f32_e32 v5, v5, v9
	v_mul_f32_e32 v6, v6, v10
	v_mul_f32_e32 v7, v7, v11
	v_mul_f32_e32 v8, v0, v12
	v_mul_f32_e32 v9, v1, v13
	v_mul_f32_e32 v10, v2, v14
	v_cvt_pk_bf16_f32 v0, v4, v5
	v_cvt_pk_bf16_f32 v1, v6, v7
	v_cvt_pk_bf16_f32 v2, v8, v9
	v_cvt_pk_bf16_f32 v3, v10, v3
	global_store_dwordx4 v[16:17], v[0:3], off offset:256
	s_cbranch_vccz .LBB0_984
	s_waitcnt vmcnt(0)
	s_cmpk_gt_u32 s25, 0xff
	s_cbranch_scc1 .LBB0_995
	s_barrier
